# pf4fu + P6 epilogue: the three sc1 status-flag loads issued after the 32 residual loads so the in-order first-use waits on the residual data are not gated by them
# speedup vs baseline: 1.0011x; 1.0011x over previous
.LBB0_1021:
	s_lshl_b32 s2, s37, 8
	s_lshl_b32 s0, s38, 5
	v_add_u32_e32 v134, s2, v210
	s_or_b32 s0, s0, s41
	v_lshrrev_b32_e32 v130, 2, v211
	v_ashrrev_i32_e32 v135, 31, v134
	v_and_or_b32 v216, v130, 12, s0
	v_lshlrev_b64 v[136:137], 11, v[134:135]
	v_lshl_add_u64 v[136:137], s[64:65], 0, v[136:137]
	v_lshlrev_b32_e32 v130, 1, v216
	v_lshl_add_u64 v[136:137], v[136:137], 0, v[130:131]
	s_barrier
	global_load_dwordx2 v[218:219], v[136:137], off
	global_load_dwordx2 v[220:221], v[136:137], off offset:32
	global_load_dwordx2 v[222:223], v[136:137], off offset:256
	global_load_dwordx2 v[224:225], v[136:137], off offset:288
	v_add_u32_e32 v136, 16, v134
	v_ashrrev_i32_e32 v137, 31, v136
	v_lshlrev_b64 v[138:139], 11, v[136:137]
	v_lshl_add_u64 v[138:139], s[64:65], 0, v[138:139]
	v_lshl_add_u64 v[138:139], v[138:139], 0, v[130:131]
	global_load_dwordx2 v[204:205], v[138:139], off
	global_load_dwordx2 v[202:203], v[138:139], off offset:32
	global_load_dwordx2 v[200:201], v[138:139], off offset:256
	global_load_dwordx2 v[198:199], v[138:139], off offset:288
	v_add_u32_e32 v138, 32, v134
	v_ashrrev_i32_e32 v139, 31, v138
	v_lshlrev_b64 v[140:141], 11, v[138:139]
	v_lshl_add_u64 v[140:141], s[64:65], 0, v[140:141]
	v_lshl_add_u64 v[140:141], v[140:141], 0, v[130:131]
	global_load_dwordx2 v[196:197], v[140:141], off
	global_load_dwordx2 v[194:195], v[140:141], off offset:32
	global_load_dwordx2 v[192:193], v[140:141], off offset:256
	global_load_dwordx2 v[190:191], v[140:141], off offset:288
	v_add_u32_e32 v140, 48, v134
	v_ashrrev_i32_e32 v141, 31, v140
	v_lshlrev_b64 v[142:143], 11, v[140:141]
	v_lshl_add_u64 v[142:143], s[64:65], 0, v[142:143]
	v_lshl_add_u64 v[142:143], v[142:143], 0, v[130:131]
	global_load_dwordx2 v[188:189], v[142:143], off
	global_load_dwordx2 v[186:187], v[142:143], off offset:32
	global_load_dwordx2 v[184:185], v[142:143], off offset:256
	global_load_dwordx2 v[182:183], v[142:143], off offset:288
	v_add_u32_e32 v142, 0x80, v134
	v_ashrrev_i32_e32 v143, 31, v142
	v_lshlrev_b64 v[144:145], 11, v[142:143]
	v_lshl_add_u64 v[144:145], s[64:65], 0, v[144:145]
	v_lshl_add_u64 v[144:145], v[144:145], 0, v[130:131]
	global_load_dwordx2 v[180:181], v[144:145], off
	global_load_dwordx2 v[178:179], v[144:145], off offset:32
	global_load_dwordx2 v[176:177], v[144:145], off offset:256
	global_load_dwordx2 v[174:175], v[144:145], off offset:288
	v_add_u32_e32 v144, 0x90, v134
	v_ashrrev_i32_e32 v145, 31, v144
	v_lshlrev_b64 v[146:147], 11, v[144:145]
	v_lshl_add_u64 v[146:147], s[64:65], 0, v[146:147]
	v_lshl_add_u64 v[146:147], v[146:147], 0, v[130:131]
	global_load_dwordx2 v[172:173], v[146:147], off
	global_load_dwordx2 v[170:171], v[146:147], off offset:32
	global_load_dwordx2 v[168:169], v[146:147], off offset:256
	global_load_dwordx2 v[166:167], v[146:147], off offset:288
	v_add_u32_e32 v146, 0xa0, v134
	v_ashrrev_i32_e32 v147, 31, v146
	v_lshlrev_b64 v[148:149], 11, v[146:147]
	v_lshl_add_u64 v[148:149], s[64:65], 0, v[148:149]
	v_lshl_add_u64 v[148:149], v[148:149], 0, v[130:131]
	global_load_dwordx2 v[164:165], v[148:149], off
	global_load_dwordx2 v[162:163], v[148:149], off offset:32
	global_load_dwordx2 v[160:161], v[148:149], off offset:256
	global_load_dwordx2 v[158:159], v[148:149], off offset:288
	v_add_u32_e32 v148, 0xb0, v134
	v_ashrrev_i32_e32 v149, 31, v148
	v_lshlrev_b64 v[150:151], 11, v[148:149]
	v_lshl_add_u64 v[150:151], s[64:65], 0, v[150:151]
	v_lshl_add_u64 v[150:151], v[150:151], 0, v[130:131]
	global_load_dwordx2 v[156:157], v[150:151], off
	global_load_dwordx2 v[154:155], v[150:151], off offset:32
	global_load_dwordx2 v[152:153], v[150:151], off offset:256
	s_nop 0
	global_load_dwordx2 v[150:151], v[150:151], off offset:288
	global_load_dword v214, v131, s[70:71] sc1
	global_load_dword v215, v131, s[10:11] sc1
	global_load_dword v213, v131, s[12:13] sc1
	v_and_b32_e32 v217, 64, v1
	v_xor_b32_e32 v130, 16, v1
	s_lshl_b32 s0, s38, 2
	s_add_i32 s3, s0, 0
	s_waitcnt vmcnt(34)
	v_lshlrev_b32_e32 v226, 16, v218
	v_and_b32_e32 v227, 0xffff0000, v218
	v_lshlrev_b32_e32 v218, 16, v219
	v_and_b32_e32 v219, 0xffff0000, v219
	v_pk_add_f32 v[128:129], v[128:129], v[218:219]
	s_waitcnt vmcnt(33)
	v_lshlrev_b32_e32 v218, 16, v220
	v_and_b32_e32 v219, 0xffff0000, v220
	v_pk_add_f32 v[122:123], v[122:123], v[218:219]
	s_waitcnt vmcnt(32)
	v_lshlrev_b32_e32 v218, 16, v222
	v_and_b32_e32 v219, 0xffff0000, v222
	v_pk_add_f32 v[118:119], v[118:119], v[218:219]
	s_waitcnt vmcnt(31)
	v_lshlrev_b32_e32 v218, 16, v224
	v_and_b32_e32 v219, 0xffff0000, v224
	v_pk_add_f32 v[114:115], v[114:115], v[218:219]
	v_add_u32_e32 v218, 64, v217
	v_cmp_lt_i32_e32 vcc, v130, v218
	v_pk_add_f32 v[126:127], v[126:127], v[226:227]
	v_lshlrev_b32_e32 v220, 16, v221
	v_and_b32_e32 v221, 0xffff0000, v221
	v_cndmask_b32_e32 v130, v1, v130, vcc
	v_pk_add_f32 v[124:125], v[124:125], v[220:221]
	v_lshlrev_b32_e32 v220, 16, v223
	v_and_b32_e32 v221, 0xffff0000, v223
	v_lshlrev_b32_e32 v217, 2, v130
	v_mul_f32_e32 v130, v127, v127
	v_mul_f32_e32 v219, v129, v129
	v_pk_add_f32 v[120:121], v[120:121], v[220:221]
	v_lshlrev_b32_e32 v220, 16, v225
	v_and_b32_e32 v221, 0xffff0000, v225
	v_fmac_f32_e32 v130, v126, v126
	v_fmac_f32_e32 v219, v128, v128
	v_pk_add_f32 v[116:117], v[116:117], v[220:221]
	v_add_f32_e32 v130, v130, v219
	v_mul_f32_e32 v219, v123, v123
	v_mul_f32_e32 v220, v125, v125
	v_fmac_f32_e32 v219, v122, v122
	v_fmac_f32_e32 v220, v124, v124
	v_add_f32_e32 v219, v219, v220
	v_add_f32_e32 v130, v130, v219
	v_mul_f32_e32 v219, v119, v119
	v_mul_f32_e32 v220, v121, v121
	v_fmac_f32_e32 v219, v118, v118
	v_fmac_f32_e32 v220, v120, v120
	v_add_f32_e32 v219, v219, v220
	v_add_f32_e32 v130, v130, v219
	v_mul_f32_e32 v219, v115, v115
	v_mul_f32_e32 v220, v117, v117
	v_fmac_f32_e32 v219, v114, v114
	v_fmac_f32_e32 v220, v116, v116
	v_add_f32_e32 v219, v219, v220
	v_add_f32_e32 v130, v130, v219
	ds_bpermute_b32 v219, v217, v130
	v_xor_b32_e32 v220, 32, v1
	v_cmp_lt_i32_e32 vcc, v220, v218
	s_waitcnt lgkmcnt(0)
	v_add_f32_e32 v219, v130, v219
	v_cndmask_b32_e32 v218, v1, v220, vcc
	v_lshlrev_b32_e32 v218, 2, v218
	ds_bpermute_b32 v220, v218, v219
	v_and_b32_e32 v130, 63, v211
	v_cmp_gt_u32_e32 vcc, 16, v130
	s_and_saveexec_b64 s[0:1], vcc
	s_cbranch_execz .LBB0_1023
	s_lshl_b32 s4, s35, 10
	s_add_i32 s4, s3, s4
	v_lshl_add_u32 v221, v212, 4, s4
	s_waitcnt lgkmcnt(0)
	v_add_f32_e32 v219, v219, v220
	ds_write_b32 v221, v219
.LBB0_1023:
	s_or_b64 exec, exec, s[0:1]
	s_waitcnt lgkmcnt(0)
	s_waitcnt vmcnt(30)
	v_lshlrev_b32_e32 v220, 16, v204
	v_and_b32_e32 v221, 0xffff0000, v204
	v_lshlrev_b32_e32 v204, 16, v205
	v_and_b32_e32 v205, 0xffff0000, v205
	v_pk_add_f32 v[112:113], v[112:113], v[204:205]
	s_waitcnt vmcnt(29)
	v_lshlrev_b32_e32 v204, 16, v202
	v_and_b32_e32 v205, 0xffff0000, v202
	v_lshlrev_b32_e32 v202, 16, v203
	v_and_b32_e32 v203, 0xffff0000, v203
	v_pk_add_f32 v[108:109], v[108:109], v[202:203]
	s_waitcnt vmcnt(28)
	v_lshlrev_b32_e32 v202, 16, v200
	v_and_b32_e32 v203, 0xffff0000, v200
	v_lshlrev_b32_e32 v200, 16, v201
	v_and_b32_e32 v201, 0xffff0000, v201
	v_pk_add_f32 v[110:111], v[110:111], v[220:221]
	v_pk_add_f32 v[104:105], v[104:105], v[200:201]
	s_waitcnt vmcnt(27)
	v_lshlrev_b32_e32 v200, 16, v198
	v_and_b32_e32 v201, 0xffff0000, v198
	v_lshlrev_b32_e32 v198, 16, v199
	v_and_b32_e32 v199, 0xffff0000, v199
	v_pk_add_f32 v[100:101], v[100:101], v[198:199]
	v_mul_f32_e32 v198, v111, v111
	v_mul_f32_e32 v199, v113, v113
	v_pk_add_f32 v[106:107], v[106:107], v[204:205]
	v_fmac_f32_e32 v198, v110, v110
	v_fmac_f32_e32 v199, v112, v112
	v_pk_add_f32 v[98:99], v[98:99], v[200:201]
	v_add_f32_e32 v198, v198, v199
	v_mul_f32_e32 v199, v107, v107
	v_mul_f32_e32 v200, v109, v109
	v_fmac_f32_e32 v199, v106, v106
	v_fmac_f32_e32 v200, v108, v108
	v_pk_add_f32 v[102:103], v[102:103], v[202:203]
	v_add_f32_e32 v199, v199, v200
	v_add_f32_e32 v198, v198, v199
	v_mul_f32_e32 v199, v103, v103
	v_mul_f32_e32 v200, v105, v105
	v_fmac_f32_e32 v199, v102, v102
	v_fmac_f32_e32 v200, v104, v104
	v_add_f32_e32 v199, v199, v200
	v_add_f32_e32 v198, v198, v199
	v_mul_f32_e32 v199, v99, v99
	v_mul_f32_e32 v200, v101, v101
	v_fmac_f32_e32 v199, v98, v98
	v_fmac_f32_e32 v200, v100, v100
	v_add_f32_e32 v199, v199, v200
	v_add_f32_e32 v198, v198, v199
	ds_bpermute_b32 v199, v217, v198
	s_waitcnt lgkmcnt(0)
	v_add_f32_e32 v198, v198, v199
	ds_bpermute_b32 v199, v218, v198
	s_and_saveexec_b64 s[0:1], vcc
	s_cbranch_execz .LBB0_1025
	s_lshl_b32 s4, s35, 10
	s_add_i32 s4, s3, s4
	v_lshl_add_u32 v200, v212, 4, s4
	s_waitcnt lgkmcnt(0)
	v_add_f32_e32 v198, v198, v199
	ds_write_b32 v200, v198 offset:256
.LBB0_1025:
	s_or_b64 exec, exec, s[0:1]
	s_waitcnt vmcnt(26)
	v_lshlrev_b32_e32 v198, 16, v196
	s_waitcnt lgkmcnt(0)
	v_and_b32_e32 v199, 0xffff0000, v196
	v_lshlrev_b32_e32 v196, 16, v197
	v_and_b32_e32 v197, 0xffff0000, v197
	v_pk_add_f32 v[96:97], v[96:97], v[196:197]
	s_waitcnt vmcnt(25)
	v_lshlrev_b32_e32 v196, 16, v194
	v_and_b32_e32 v197, 0xffff0000, v194
	v_lshlrev_b32_e32 v194, 16, v195
	v_and_b32_e32 v195, 0xffff0000, v195
	v_pk_add_f32 v[92:93], v[92:93], v[194:195]
	s_waitcnt vmcnt(24)
	v_lshlrev_b32_e32 v194, 16, v192
	v_and_b32_e32 v195, 0xffff0000, v192
	v_lshlrev_b32_e32 v192, 16, v193
	v_and_b32_e32 v193, 0xffff0000, v193
	v_pk_add_f32 v[94:95], v[94:95], v[198:199]
	v_pk_add_f32 v[88:89], v[88:89], v[192:193]
	s_waitcnt vmcnt(23)
	v_lshlrev_b32_e32 v192, 16, v190
	v_and_b32_e32 v193, 0xffff0000, v190
	v_lshlrev_b32_e32 v190, 16, v191
	v_and_b32_e32 v191, 0xffff0000, v191
	v_pk_add_f32 v[84:85], v[84:85], v[190:191]
	v_mul_f32_e32 v190, v95, v95
	v_mul_f32_e32 v191, v97, v97
	v_pk_add_f32 v[90:91], v[90:91], v[196:197]
	v_fmac_f32_e32 v190, v94, v94
	v_fmac_f32_e32 v191, v96, v96
	v_pk_add_f32 v[82:83], v[82:83], v[192:193]
	v_add_f32_e32 v190, v190, v191
	v_mul_f32_e32 v191, v91, v91
	v_mul_f32_e32 v192, v93, v93
	v_fmac_f32_e32 v191, v90, v90
	v_fmac_f32_e32 v192, v92, v92
	v_pk_add_f32 v[86:87], v[86:87], v[194:195]
	v_add_f32_e32 v191, v191, v192
	v_add_f32_e32 v190, v190, v191
	v_mul_f32_e32 v191, v87, v87
	v_mul_f32_e32 v192, v89, v89
	v_fmac_f32_e32 v191, v86, v86
	v_fmac_f32_e32 v192, v88, v88
	v_add_f32_e32 v191, v191, v192
	v_add_f32_e32 v190, v190, v191
	v_mul_f32_e32 v191, v83, v83
	v_mul_f32_e32 v192, v85, v85
	v_fmac_f32_e32 v191, v82, v82
	v_fmac_f32_e32 v192, v84, v84
	v_add_f32_e32 v191, v191, v192
	v_add_f32_e32 v190, v190, v191
	ds_bpermute_b32 v191, v217, v190
	s_waitcnt lgkmcnt(0)
	v_add_f32_e32 v190, v190, v191
	ds_bpermute_b32 v191, v218, v190
	s_and_saveexec_b64 s[0:1], vcc
	s_cbranch_execz .LBB0_1027
	s_lshl_b32 s4, s35, 10
	s_add_i32 s4, s3, s4
	v_lshl_add_u32 v192, v212, 4, s4
	s_waitcnt lgkmcnt(0)
	v_add_f32_e32 v190, v190, v191
	ds_write_b32 v192, v190 offset:512
.LBB0_1027:
	s_or_b64 exec, exec, s[0:1]
	s_waitcnt vmcnt(22)
	v_lshlrev_b32_e32 v190, 16, v188
	s_waitcnt lgkmcnt(0)
	v_and_b32_e32 v191, 0xffff0000, v188
	v_lshlrev_b32_e32 v188, 16, v189
	v_and_b32_e32 v189, 0xffff0000, v189
	v_pk_add_f32 v[80:81], v[80:81], v[188:189]
	s_waitcnt vmcnt(21)
	v_lshlrev_b32_e32 v188, 16, v186
	v_and_b32_e32 v189, 0xffff0000, v186
	v_lshlrev_b32_e32 v186, 16, v187
	v_and_b32_e32 v187, 0xffff0000, v187
	v_pk_add_f32 v[76:77], v[76:77], v[186:187]
	s_waitcnt vmcnt(20)
	v_lshlrev_b32_e32 v186, 16, v184
	v_and_b32_e32 v187, 0xffff0000, v184
	v_lshlrev_b32_e32 v184, 16, v185
	v_and_b32_e32 v185, 0xffff0000, v185
	v_pk_add_f32 v[78:79], v[78:79], v[190:191]
	v_pk_add_f32 v[72:73], v[72:73], v[184:185]
	s_waitcnt vmcnt(19)
	v_lshlrev_b32_e32 v184, 16, v182
	v_and_b32_e32 v185, 0xffff0000, v182
	v_lshlrev_b32_e32 v182, 16, v183
	v_and_b32_e32 v183, 0xffff0000, v183
	v_pk_add_f32 v[68:69], v[68:69], v[182:183]
	v_mul_f32_e32 v182, v79, v79
	v_mul_f32_e32 v183, v81, v81
	v_pk_add_f32 v[74:75], v[74:75], v[188:189]
	v_fmac_f32_e32 v182, v78, v78
	v_fmac_f32_e32 v183, v80, v80
	v_pk_add_f32 v[66:67], v[66:67], v[184:185]
	v_add_f32_e32 v182, v182, v183
	v_mul_f32_e32 v183, v75, v75
	v_mul_f32_e32 v184, v77, v77
	v_fmac_f32_e32 v183, v74, v74
	v_fmac_f32_e32 v184, v76, v76
	v_pk_add_f32 v[70:71], v[70:71], v[186:187]
	v_add_f32_e32 v183, v183, v184
	v_add_f32_e32 v182, v182, v183
	v_mul_f32_e32 v183, v71, v71
	v_mul_f32_e32 v184, v73, v73
	v_fmac_f32_e32 v183, v70, v70
	v_fmac_f32_e32 v184, v72, v72
	v_add_f32_e32 v183, v183, v184
	v_add_f32_e32 v182, v182, v183
	v_mul_f32_e32 v183, v67, v67
	v_mul_f32_e32 v184, v69, v69
	v_fmac_f32_e32 v183, v66, v66
	v_fmac_f32_e32 v184, v68, v68
	v_add_f32_e32 v183, v183, v184
	v_add_f32_e32 v182, v182, v183
	ds_bpermute_b32 v183, v217, v182
	s_waitcnt lgkmcnt(0)
	v_add_f32_e32 v182, v182, v183
	ds_bpermute_b32 v183, v218, v182
	s_and_saveexec_b64 s[0:1], vcc
	s_cbranch_execz .LBB0_1029
	s_lshl_b32 s4, s35, 10
	s_add_i32 s4, s3, s4
	v_lshl_add_u32 v184, v212, 4, s4
	s_waitcnt lgkmcnt(0)
	v_add_f32_e32 v182, v182, v183
	ds_write_b32 v184, v182 offset:768
.LBB0_1029:
	s_or_b64 exec, exec, s[0:1]
	s_waitcnt vmcnt(18)
	v_lshlrev_b32_e32 v182, 16, v180
	s_waitcnt lgkmcnt(0)
	v_and_b32_e32 v183, 0xffff0000, v180
	v_lshlrev_b32_e32 v180, 16, v181
	v_and_b32_e32 v181, 0xffff0000, v181
	v_pk_add_f32 v[64:65], v[64:65], v[180:181]
	s_waitcnt vmcnt(17)
	v_lshlrev_b32_e32 v180, 16, v178
	v_and_b32_e32 v181, 0xffff0000, v178
	v_lshlrev_b32_e32 v178, 16, v179
	v_and_b32_e32 v179, 0xffff0000, v179
	v_pk_add_f32 v[60:61], v[60:61], v[178:179]
	s_waitcnt vmcnt(16)
	v_lshlrev_b32_e32 v178, 16, v176
	v_and_b32_e32 v179, 0xffff0000, v176
	v_lshlrev_b32_e32 v176, 16, v177
	v_and_b32_e32 v177, 0xffff0000, v177
	v_pk_add_f32 v[62:63], v[62:63], v[182:183]
	v_pk_add_f32 v[56:57], v[56:57], v[176:177]
	s_waitcnt vmcnt(15)
	v_lshlrev_b32_e32 v176, 16, v174
	v_and_b32_e32 v177, 0xffff0000, v174
	v_lshlrev_b32_e32 v174, 16, v175
	v_and_b32_e32 v175, 0xffff0000, v175
	v_pk_add_f32 v[52:53], v[52:53], v[174:175]
	v_mul_f32_e32 v174, v63, v63
	v_mul_f32_e32 v175, v65, v65
	v_pk_add_f32 v[58:59], v[58:59], v[180:181]
	v_fmac_f32_e32 v174, v62, v62
	v_fmac_f32_e32 v175, v64, v64
	v_pk_add_f32 v[50:51], v[50:51], v[176:177]
	v_add_f32_e32 v174, v174, v175
	v_mul_f32_e32 v175, v59, v59
	v_mul_f32_e32 v176, v61, v61
	v_fmac_f32_e32 v175, v58, v58
	v_fmac_f32_e32 v176, v60, v60
	v_pk_add_f32 v[54:55], v[54:55], v[178:179]
	v_add_f32_e32 v175, v175, v176
	v_add_f32_e32 v174, v174, v175
	v_mul_f32_e32 v175, v55, v55
	v_mul_f32_e32 v176, v57, v57
	v_fmac_f32_e32 v175, v54, v54
	v_fmac_f32_e32 v176, v56, v56
	v_add_f32_e32 v175, v175, v176
	v_add_f32_e32 v174, v174, v175
	v_mul_f32_e32 v175, v51, v51
	v_mul_f32_e32 v176, v53, v53
	v_fmac_f32_e32 v175, v50, v50
	v_fmac_f32_e32 v176, v52, v52
	v_add_f32_e32 v175, v175, v176
	v_add_f32_e32 v174, v174, v175
	ds_bpermute_b32 v175, v217, v174
	s_waitcnt lgkmcnt(0)
	v_add_f32_e32 v174, v174, v175
	ds_bpermute_b32 v175, v218, v174
	s_and_saveexec_b64 s[0:1], vcc
	s_cbranch_execz .LBB0_1031
	s_lshl_b32 s4, s35, 10
	s_add_i32 s4, s3, s4
	v_lshl_add_u32 v176, v212, 4, s4
	s_waitcnt lgkmcnt(0)
	v_add_f32_e32 v174, v174, v175
	ds_write_b32 v176, v174 offset:2048
.LBB0_1031:
	s_or_b64 exec, exec, s[0:1]
	s_waitcnt vmcnt(14)
	v_lshlrev_b32_e32 v174, 16, v172
	s_waitcnt lgkmcnt(0)
	v_and_b32_e32 v175, 0xffff0000, v172
	v_lshlrev_b32_e32 v172, 16, v173
	v_and_b32_e32 v173, 0xffff0000, v173
	v_pk_add_f32 v[48:49], v[48:49], v[172:173]
	s_waitcnt vmcnt(13)
	v_lshlrev_b32_e32 v172, 16, v170
	v_and_b32_e32 v173, 0xffff0000, v170
	v_lshlrev_b32_e32 v170, 16, v171
	v_and_b32_e32 v171, 0xffff0000, v171
	v_pk_add_f32 v[44:45], v[44:45], v[170:171]
	s_waitcnt vmcnt(12)
	v_lshlrev_b32_e32 v170, 16, v168
	v_and_b32_e32 v171, 0xffff0000, v168
	v_lshlrev_b32_e32 v168, 16, v169
	v_and_b32_e32 v169, 0xffff0000, v169
	v_pk_add_f32 v[46:47], v[46:47], v[174:175]
	v_pk_add_f32 v[40:41], v[40:41], v[168:169]
	s_waitcnt vmcnt(11)
	v_lshlrev_b32_e32 v168, 16, v166
	v_and_b32_e32 v169, 0xffff0000, v166
	v_lshlrev_b32_e32 v166, 16, v167
	v_and_b32_e32 v167, 0xffff0000, v167
	v_pk_add_f32 v[36:37], v[36:37], v[166:167]
	v_mul_f32_e32 v166, v47, v47
	v_mul_f32_e32 v167, v49, v49
	v_pk_add_f32 v[42:43], v[42:43], v[172:173]
	v_fmac_f32_e32 v166, v46, v46
	v_fmac_f32_e32 v167, v48, v48
	v_pk_add_f32 v[34:35], v[34:35], v[168:169]
	v_add_f32_e32 v166, v166, v167
	v_mul_f32_e32 v167, v43, v43
	v_mul_f32_e32 v168, v45, v45
	v_fmac_f32_e32 v167, v42, v42
	v_fmac_f32_e32 v168, v44, v44
	v_pk_add_f32 v[38:39], v[38:39], v[170:171]
	v_add_f32_e32 v167, v167, v168
	v_add_f32_e32 v166, v166, v167
	v_mul_f32_e32 v167, v39, v39
	v_mul_f32_e32 v168, v41, v41
	v_fmac_f32_e32 v167, v38, v38
	v_fmac_f32_e32 v168, v40, v40
	v_add_f32_e32 v167, v167, v168
	v_add_f32_e32 v166, v166, v167
	v_mul_f32_e32 v167, v35, v35
	v_mul_f32_e32 v168, v37, v37
	v_fmac_f32_e32 v167, v34, v34
	v_fmac_f32_e32 v168, v36, v36
	v_add_f32_e32 v167, v167, v168
	v_add_f32_e32 v166, v166, v167
	ds_bpermute_b32 v167, v217, v166
	s_waitcnt lgkmcnt(0)
	v_add_f32_e32 v166, v166, v167
	ds_bpermute_b32 v167, v218, v166
	s_and_saveexec_b64 s[0:1], vcc
	s_cbranch_execz .LBB0_1033
	s_lshl_b32 s4, s35, 10
	s_add_i32 s4, s3, s4
	v_lshl_add_u32 v168, v212, 4, s4
	s_waitcnt lgkmcnt(0)
	v_add_f32_e32 v166, v166, v167
	ds_write_b32 v168, v166 offset:2304
.LBB0_1033:
	s_or_b64 exec, exec, s[0:1]
	s_waitcnt vmcnt(10)
	v_lshlrev_b32_e32 v166, 16, v164
	s_waitcnt lgkmcnt(0)
	v_and_b32_e32 v167, 0xffff0000, v164
	v_lshlrev_b32_e32 v164, 16, v165
	v_and_b32_e32 v165, 0xffff0000, v165
	v_pk_add_f32 v[32:33], v[32:33], v[164:165]
	s_waitcnt vmcnt(9)
	v_lshlrev_b32_e32 v164, 16, v162
	v_and_b32_e32 v165, 0xffff0000, v162
	v_lshlrev_b32_e32 v162, 16, v163
	v_and_b32_e32 v163, 0xffff0000, v163
	v_pk_add_f32 v[28:29], v[28:29], v[162:163]
	s_waitcnt vmcnt(8)
	v_lshlrev_b32_e32 v162, 16, v160
	v_and_b32_e32 v163, 0xffff0000, v160
	v_lshlrev_b32_e32 v160, 16, v161
	v_and_b32_e32 v161, 0xffff0000, v161
	v_pk_add_f32 v[30:31], v[30:31], v[166:167]
	v_pk_add_f32 v[24:25], v[24:25], v[160:161]
	s_waitcnt vmcnt(7)
	v_lshlrev_b32_e32 v160, 16, v158
	v_and_b32_e32 v161, 0xffff0000, v158
	v_lshlrev_b32_e32 v158, 16, v159
	v_and_b32_e32 v159, 0xffff0000, v159
	v_pk_add_f32 v[20:21], v[20:21], v[158:159]
	v_mul_f32_e32 v158, v31, v31
	v_mul_f32_e32 v159, v33, v33
	v_pk_add_f32 v[26:27], v[26:27], v[164:165]
	v_fmac_f32_e32 v158, v30, v30
	v_fmac_f32_e32 v159, v32, v32
	v_pk_add_f32 v[18:19], v[18:19], v[160:161]
	v_add_f32_e32 v158, v158, v159
	v_mul_f32_e32 v159, v27, v27
	v_mul_f32_e32 v160, v29, v29
	v_fmac_f32_e32 v159, v26, v26
	v_fmac_f32_e32 v160, v28, v28
	v_pk_add_f32 v[22:23], v[22:23], v[162:163]
	v_add_f32_e32 v159, v159, v160
	v_add_f32_e32 v158, v158, v159
	v_mul_f32_e32 v159, v23, v23
	v_mul_f32_e32 v160, v25, v25
	v_fmac_f32_e32 v159, v22, v22
	v_fmac_f32_e32 v160, v24, v24
	v_add_f32_e32 v159, v159, v160
	v_add_f32_e32 v158, v158, v159
	v_mul_f32_e32 v159, v19, v19
	v_mul_f32_e32 v160, v21, v21
	v_fmac_f32_e32 v159, v18, v18
	v_fmac_f32_e32 v160, v20, v20
	v_add_f32_e32 v159, v159, v160
	v_add_f32_e32 v158, v158, v159
	ds_bpermute_b32 v159, v217, v158
	s_waitcnt lgkmcnt(0)
	v_add_f32_e32 v158, v158, v159
	ds_bpermute_b32 v159, v218, v158
	s_and_saveexec_b64 s[0:1], vcc
	s_cbranch_execz .LBB0_1035
	s_lshl_b32 s4, s35, 10
	s_add_i32 s4, s3, s4
	v_lshl_add_u32 v160, v212, 4, s4
	s_waitcnt lgkmcnt(0)
	v_add_f32_e32 v158, v158, v159
	ds_write_b32 v160, v158 offset:2560
.LBB0_1035:
	s_or_b64 exec, exec, s[0:1]
	s_waitcnt vmcnt(6)
	v_lshlrev_b32_e32 v158, 16, v156
	s_waitcnt lgkmcnt(0)
	v_and_b32_e32 v159, 0xffff0000, v156
	v_pk_add_f32 v[164:165], v[14:15], v[158:159]
	s_waitcnt vmcnt(5)
	v_lshlrev_b32_e32 v14, 16, v154
	v_and_b32_e32 v15, 0xffff0000, v154
	v_lshlrev_b32_e32 v156, 16, v157
	v_and_b32_e32 v157, 0xffff0000, v157
	v_pk_add_f32 v[162:163], v[10:11], v[14:15]
	s_waitcnt vmcnt(4)
	v_lshlrev_b32_e32 v10, 16, v152
	v_and_b32_e32 v11, 0xffff0000, v152
	v_pk_add_f32 v[160:161], v[16:17], v[156:157]
	v_lshlrev_b32_e32 v16, 16, v155
	v_and_b32_e32 v17, 0xffff0000, v155
	v_pk_add_f32 v[158:159], v[6:7], v[10:11]
	s_waitcnt vmcnt(3)
	v_lshlrev_b32_e32 v6, 16, v150
	v_and_b32_e32 v7, 0xffff0000, v150
	v_pk_add_f32 v[154:155], v[12:13], v[16:17]
	v_lshlrev_b32_e32 v12, 16, v153
	v_and_b32_e32 v13, 0xffff0000, v153
	v_pk_add_f32 v[156:157], v[2:3], v[6:7]
	v_mul_f32_e32 v2, v165, v165
	v_mul_f32_e32 v3, v161, v161
	v_pk_add_f32 v[152:153], v[8:9], v[12:13]
	v_lshlrev_b32_e32 v8, 16, v151
	v_and_b32_e32 v9, 0xffff0000, v151
	v_fmac_f32_e32 v2, v164, v164
	v_fmac_f32_e32 v3, v160, v160
	v_pk_add_f32 v[150:151], v[4:5], v[8:9]
	v_add_f32_e32 v2, v2, v3
	v_mul_f32_e32 v3, v163, v163
	v_mul_f32_e32 v4, v155, v155
	v_fmac_f32_e32 v3, v162, v162
	v_fmac_f32_e32 v4, v154, v154
	v_add_f32_e32 v3, v3, v4
	v_add_f32_e32 v2, v2, v3
	v_mul_f32_e32 v3, v159, v159
	v_mul_f32_e32 v4, v153, v153
	v_fmac_f32_e32 v3, v158, v158
	v_fmac_f32_e32 v4, v152, v152
	v_add_f32_e32 v3, v3, v4
	v_add_f32_e32 v2, v2, v3
	v_mul_f32_e32 v3, v157, v157
	v_mul_f32_e32 v4, v151, v151
	v_fmac_f32_e32 v3, v156, v156
	v_fmac_f32_e32 v4, v150, v150
	v_add_f32_e32 v3, v3, v4
	v_add_f32_e32 v2, v2, v3
	ds_bpermute_b32 v3, v217, v2
	s_waitcnt lgkmcnt(0)
	v_add_f32_e32 v2, v2, v3
	ds_bpermute_b32 v3, v218, v2
	s_and_saveexec_b64 s[0:1], vcc
	s_cbranch_execz .LBB0_1037
	s_lshl_b32 s4, s35, 10
	s_add_i32 s3, s3, s4
	v_lshl_add_u32 v4, v212, 4, s3
	s_waitcnt lgkmcnt(0)
	v_add_f32_e32 v2, v2, v3
	ds_write_b32 v4, v2 offset:2816
